# same as previous but the priority raise goes to the first-dispatched workgroup of each CU
# baseline (speedup 1.0000x reference)
; template <int NJ>
; __device__ __forceinline__ void gemm_tile(const f16* __restrict__ A, int lda, const f16* __restrict__ Bt, int ldb,
;                                           int K, f32x4 (&acc)[4][NJ], f16* sA, f16* sB, const int tid) {
;     ...
;   G_LOAD(ra0, rb0, 0)
;   if (K > 64) G_LOAD(ra1, rb1, 64)
;   __syncthreads();
;   G_STORE(ra0, rb0, 0)
;   if (K > 128) G_LOAD(ra0, rb0, 128)
;   __syncthreads();
; __device__ __forceinline__ void phase_g1(const Params& p, int l, f16* smem) {
;     ...
;   for (int t = blockIdx.x; t < MT * NT; t += gridDim.x) {
;     int m0 = (t / NT) * 128, n0 = (t % NT) * 128;
;     f32x4 acc[4][4];
;     zero_acc<4>(acc);
;     gemm_tile<4>(H + (size_t)m0 * DM, DM, W + (size_t)n0 * DM, DM, DM, acc, sA, sB, TIDX(p));
.Lxm_done_g1:
	s_lshl_b64 s[6:7], s[14:15], 11
	v_lshl_add_u64 v[156:157], v[154:155], 0, s[6:7]
	v_add_co_u32_e32 v4, vcc, s94, v156
	s_lshl_b32 s16, s21, 7
	s_nop 0
	v_addc_co_u32_e32 v5, vcc, 0, v157, vcc
	v_add_co_u32_e32 v6, vcc, s72, v156
	s_ashr_i32 s17, s16, 31
	s_nop 0
	v_addc_co_u32_e32 v7, vcc, 0, v157, vcc
	s_lshl_b64 s[8:9], s[16:17], 11
	v_add_co_u32_e32 v8, vcc, s73, v156
	v_lshl_add_u64 v[158:159], v[152:153], 0, s[8:9]
	s_nop 0
	v_addc_co_u32_e32 v9, vcc, 0, v157, vcc
	v_add_co_u32_e32 v10, vcc, s94, v158
	global_load_dwordx4 v[18:21], v[156:157], off
	s_nop 0
	v_addc_co_u32_e32 v11, vcc, 0, v159, vcc
	v_add_co_u32_e32 v12, vcc, s72, v158
	global_load_dwordx4 v[22:25], v[4:5], off
	global_load_dwordx4 v[26:29], v[6:7], off
	v_addc_co_u32_e32 v13, vcc, 0, v159, vcc
	v_add_co_u32_e32 v14, vcc, s73, v158
	global_load_dwordx4 v[30:33], v[8:9], off
	global_load_dwordx4 v[38:41], v[10:11], off
	v_addc_co_u32_e32 v15, vcc, 0, v159, vcc
	global_load_dwordx4 v[34:37], v[158:159], off
	global_load_dwordx4 v[42:45], v[12:13], off
	global_load_dwordx4 v[46:49], v[14:15], off
	global_load_dwordx4 v[68:71], v[156:157], off offset:128
	global_load_dwordx4 v[76:79], v[4:5], off offset:128
	global_load_dwordx4 v[80:83], v[6:7], off offset:128
	global_load_dwordx4 v[84:87], v[8:9], off offset:128
	global_load_dwordx4 v[72:75], v[158:159], off offset:128
	global_load_dwordx4 v[88:91], v[10:11], off offset:128
	global_load_dwordx4 v[96:99], v[12:13], off offset:128
	global_load_dwordx4 v[100:103], v[14:15], off offset:128
	s_barrier
	global_load_dwordx4 v[108:111], v[4:5], off offset:256
	global_load_dwordx4 v[112:115], v[6:7], off offset:256
	global_load_dwordx4 v[92:95], v[156:157], off offset:256
	global_load_dwordx4 v[104:107], v[158:159], off offset:256
	global_load_dwordx4 v[116:119], v[8:9], off offset:256
	global_load_dwordx4 v[120:123], v[10:11], off offset:256
	global_load_dwordx4 v[124:127], v[12:13], off offset:256
	global_load_dwordx4 v[128:131], v[14:15], off offset:256
	v_mov_b32_e32 v4, 0
	s_mov_b32 s6, 0
	v_mov_b32_e32 v5, v4
	v_mov_b32_e32 v6, v4
	v_mov_b32_e32 v7, v4
	v_mov_b32_e32 v8, v4
	v_mov_b32_e32 v9, v4
	v_mov_b32_e32 v10, v4
	v_mov_b32_e32 v11, v4
	v_mov_b32_e32 v12, v4
	v_mov_b32_e32 v13, v4
	v_mov_b32_e32 v14, v4
	v_mov_b32_e32 v15, v4
	v_mov_b32_e32 v16, v4
	v_mov_b32_e32 v17, v4
	v_mov_b32_e32 v50, v4
	v_mov_b32_e32 v51, v4
	v_mov_b32_e32 v52, v4
	v_mov_b32_e32 v53, v4
	v_mov_b32_e32 v54, v4
	v_mov_b32_e32 v55, v4
	v_mov_b32_e32 v56, v4
	v_mov_b32_e32 v57, v4
	v_mov_b32_e32 v58, v4
	v_mov_b32_e32 v59, v4
	v_mov_b32_e32 v60, v4
	v_mov_b32_e32 v61, v4
	v_mov_b32_e32 v62, v4
	v_mov_b32_e32 v63, v4
	v_mov_b32_e32 v64, v4
	v_mov_b32_e32 v65, v4
	v_mov_b32_e32 v66, v4
	v_mov_b32_e32 v67, v4
	s_waitcnt vmcnt(23)
	ds_write_b128 v167, v[18:21]
	s_waitcnt vmcnt(22)
	ds_write_b128 v167, v[22:25] offset:4096
	s_waitcnt vmcnt(21)
	ds_write_b128 v167, v[26:29] offset:8192
	s_waitcnt vmcnt(20)
	ds_write_b128 v167, v[30:33] offset:12288
	s_waitcnt vmcnt(18)
	ds_write_b128 v167, v[34:37] offset:16384
	ds_write_b128 v167, v[38:41] offset:20480
	s_waitcnt vmcnt(17)
	ds_write_b128 v167, v[42:45] offset:24576
	s_waitcnt vmcnt(16)
	ds_write_b128 v167, v[46:49] offset:28672
	v_mov_b32_e32 v18, v4
	v_mov_b32_e32 v19, v4
	v_mov_b32_e32 v20, v4
	v_mov_b32_e32 v21, v4
	v_mov_b32_e32 v22, v4
	v_mov_b32_e32 v23, v4
	v_mov_b32_e32 v24, v4
	v_mov_b32_e32 v25, v4
	v_mov_b32_e32 v26, v4
	v_mov_b32_e32 v27, v4
	v_mov_b32_e32 v28, v4
	v_mov_b32_e32 v29, v4
	v_mov_b32_e32 v30, v4
	v_mov_b32_e32 v31, v4
	v_mov_b32_e32 v32, v4
	v_mov_b32_e32 v33, v4
	v_mov_b32_e32 v34, v4
	v_mov_b32_e32 v35, v4
	v_mov_b32_e32 v36, v4
	v_mov_b32_e32 v37, v4
	v_mov_b32_e32 v38, v4
	v_mov_b32_e32 v39, v4
	v_mov_b32_e32 v40, v4
	v_mov_b32_e32 v41, v4
	v_mov_b32_e32 v42, v4
	v_mov_b32_e32 v43, v4
	v_mov_b32_e32 v44, v4
	v_mov_b32_e32 v45, v4
	v_mov_b32_e32 v46, v4
	v_mov_b32_e32 v47, v4
	v_mov_b32_e32 v48, v4
	v_mov_b32_e32 v49, v4
	s_waitcnt lgkmcnt(0)
	s_barrier
	s_bitcmp1_b32 s95, 8
	s_cbranch_scc1 .Lprio_195
	s_setprio 1

; template <int NJ>
; __device__ __forceinline__ void gemm_tile(const f16* __restrict__ A, int lda, const f16* __restrict__ Bt, int ldb,
;                                           int K, f32x4 (&acc)[4][NJ], f16* sA, f16* sB, const int tid) {
;     ...
;   G_LOAD(ra0, rb0, 0)
;   if (K > 64) G_LOAD(ra1, rb1, 64)
;   __syncthreads();
;   G_STORE(ra0, rb0, 0)
;   if (K > 128) G_LOAD(ra0, rb0, 128)
;   __syncthreads();
; __device__ __forceinline__ void phase_gres(const Params& p, int l, const f16* A, int lda, const f16* W, int K, int gate_idx,
;                            bool first_in, f16* smem) {
;     ...
;   for (int t = blockIdx.x; t < full; t += gridDim.x)
;     gres_tile<4>(p, A, lda, W, K, mod, first_in, sA, sB, (t / NT) * 128, (t % NT) * 128);
.Lxm_g3:
	s_ashr_i32 s8, s12, 31
	s_lshr_b32 s8, s8, 29
	s_add_i32 s9, s12, s8
	s_lshl_b32 s8, s9, 4
	s_and_b32 s9, s9, 0x1fffff8
	s_and_b32 s8, s8, 0xffffff80
	s_sub_i32 s9, s12, s9
	s_lshl_b32 s12, s9, 7
	s_ashr_i32 s9, s8, 31
	s_lshl_b64 s[10:11], s[8:9], 11
	v_lshl_add_u64 v[154:155], v[148:149], 0, s[10:11]
	v_add_co_u32_e32 v2, vcc, s94, v154
	s_ashr_i32 s13, s12, 31
	s_nop 0
	v_addc_co_u32_e32 v3, vcc, 0, v155, vcc
	v_add_co_u32_e32 v4, vcc, s72, v154
	s_lshl_b64 s[14:15], s[12:13], 11
	s_nop 0
	v_addc_co_u32_e32 v5, vcc, 0, v155, vcc
	v_add_co_u32_e32 v6, vcc, s73, v154
	v_lshl_add_u64 v[156:157], v[150:151], 0, s[14:15]
	s_nop 0
	v_addc_co_u32_e32 v7, vcc, 0, v155, vcc
	v_add_co_u32_e32 v8, vcc, s94, v156
	global_load_dwordx4 v[16:19], v[154:155], off
	s_nop 0
	v_addc_co_u32_e32 v9, vcc, 0, v157, vcc
	v_add_co_u32_e32 v10, vcc, s72, v156
	global_load_dwordx4 v[20:23], v[2:3], off
	s_nop 0
	v_addc_co_u32_e32 v11, vcc, 0, v157, vcc
	v_add_co_u32_e32 v12, vcc, s73, v156
	global_load_dwordx4 v[24:27], v[4:5], off
	s_nop 0
	v_addc_co_u32_e32 v13, vcc, 0, v157, vcc
	global_load_dwordx4 v[28:31], v[6:7], off
	global_load_dwordx4 v[98:101], v[156:157], off
	global_load_dwordx4 v[102:105], v[8:9], off
	global_load_dwordx4 v[106:109], v[10:11], off
	global_load_dwordx4 v[110:113], v[12:13], off
	global_load_dwordx4 v[34:37], v[154:155], off offset:128
	global_load_dwordx4 v[42:45], v[2:3], off offset:128
	global_load_dwordx4 v[46:49], v[4:5], off offset:128
	global_load_dwordx4 v[50:53], v[6:7], off offset:128
	global_load_dwordx4 v[38:41], v[156:157], off offset:128
	global_load_dwordx4 v[54:57], v[8:9], off offset:128
	global_load_dwordx4 v[62:65], v[10:11], off offset:128
	global_load_dwordx4 v[66:69], v[12:13], off offset:128
	s_barrier
	global_load_dwordx4 v[74:77], v[2:3], off offset:256
	global_load_dwordx4 v[78:81], v[4:5], off offset:256
	global_load_dwordx4 v[58:61], v[154:155], off offset:256
	global_load_dwordx4 v[70:73], v[156:157], off offset:256
	global_load_dwordx4 v[82:85], v[6:7], off offset:256
	global_load_dwordx4 v[86:89], v[8:9], off offset:256
	global_load_dwordx4 v[90:93], v[10:11], off offset:256
	global_load_dwordx4 v[94:97], v[12:13], off offset:256
	v_mov_b32_e32 v2, 0
	s_mov_b32 s9, 0
	v_mov_b32_e32 v3, v2
	v_mov_b32_e32 v4, v2
	v_mov_b32_e32 v5, v2
	v_mov_b32_e32 v6, v2
	v_mov_b32_e32 v7, v2
	v_mov_b32_e32 v8, v2
	v_mov_b32_e32 v9, v2
	v_mov_b32_e32 v10, v2
	v_mov_b32_e32 v11, v2
	v_mov_b32_e32 v12, v2
	v_mov_b32_e32 v13, v2
	v_mov_b32_e32 v14, v2
	v_mov_b32_e32 v15, v2
	v_mov_b32_e32 v32, v2
	v_mov_b32_e32 v33, v2
	v_mov_b32_e32 v114, v2
	v_mov_b32_e32 v115, v2
	v_mov_b32_e32 v116, v2
	v_mov_b32_e32 v117, v2
	v_mov_b32_e32 v118, v2
	v_mov_b32_e32 v119, v2
	v_mov_b32_e32 v120, v2
	v_mov_b32_e32 v121, v2
	v_mov_b32_e32 v122, v2
	v_mov_b32_e32 v123, v2
	v_mov_b32_e32 v124, v2
	v_mov_b32_e32 v125, v2
	v_mov_b32_e32 v126, v2
	v_mov_b32_e32 v127, v2
	v_mov_b32_e32 v128, v2
	v_mov_b32_e32 v129, v2
	s_waitcnt vmcnt(23)
	ds_write_b128 v169, v[16:19]
	s_waitcnt vmcnt(22)
	ds_write_b128 v169, v[20:23] offset:4096
	s_waitcnt vmcnt(21)
	ds_write_b128 v169, v[24:27] offset:8192
	s_waitcnt vmcnt(20)
	ds_write_b128 v169, v[28:31] offset:12288
	s_waitcnt vmcnt(19)
	ds_write_b128 v169, v[98:101] offset:16384
	s_waitcnt vmcnt(18)
	ds_write_b128 v169, v[102:105] offset:20480
	s_waitcnt vmcnt(17)
	ds_write_b128 v169, v[106:109] offset:24576
	s_waitcnt vmcnt(16)
	ds_write_b128 v169, v[110:113] offset:28672
	v_mov_b32_e32 v16, v2
	v_mov_b32_e32 v17, v2
	v_mov_b32_e32 v18, v2
	v_mov_b32_e32 v19, v2
	v_mov_b32_e32 v20, v2
	v_mov_b32_e32 v21, v2
	v_mov_b32_e32 v22, v2
	v_mov_b32_e32 v23, v2
	v_mov_b32_e32 v24, v2
	v_mov_b32_e32 v25, v2
	v_mov_b32_e32 v26, v2
	v_mov_b32_e32 v27, v2
	v_mov_b32_e32 v28, v2
	v_mov_b32_e32 v29, v2
	v_mov_b32_e32 v30, v2
	v_mov_b32_e32 v31, v2
	v_mov_b32_e32 v98, v2
	v_mov_b32_e32 v99, v2
	v_mov_b32_e32 v100, v2
	v_mov_b32_e32 v101, v2
	v_mov_b32_e32 v102, v2
	v_mov_b32_e32 v103, v2
	v_mov_b32_e32 v104, v2
	v_mov_b32_e32 v105, v2
	v_mov_b32_e32 v106, v2
	v_mov_b32_e32 v107, v2
	v_mov_b32_e32 v108, v2
	v_mov_b32_e32 v109, v2
	v_mov_b32_e32 v110, v2
	v_mov_b32_e32 v111, v2
	v_mov_b32_e32 v112, v2
	v_mov_b32_e32 v113, v2
	s_waitcnt lgkmcnt(0)
	s_barrier
	s_bitcmp1_b32 s95, 8
	s_cbranch_scc1 .Lprio_1186
	s_setprio 1

; template <int NJ>
; __device__ __forceinline__ void gemm_tile(const f16* __restrict__ A, int lda, const f16* __restrict__ Bt, int ldb,
;                                           int K, f32x4 (&acc)[4][NJ], f16* sA, f16* sB, const int tid) {
;     ...
;   G_LOAD(ra0, rb0, 0)
;   if (K > 64) G_LOAD(ra1, rb1, 64)
;   __syncthreads();
;   G_STORE(ra0, rb0, 0)
;   if (K > 128) G_LOAD(ra0, rb0, 128)
;   __syncthreads();
; __device__ __forceinline__ void phase_g4(const Params& p, f16* smem) {
;     ...
;   for (int t = blockIdx.x; t < MT * NT; t += gridDim.x) {
;     int m0 = (t / NT) * 128, nt = t % NT;
;     f32x4 acc[4][4];
;     zero_acc<4>(acc);
;     gemm_tile<4>(H2 + (size_t)m0 * DM, DM, W + (size_t)nt * 128 * DM, DM, DM, acc, sA, sB, TIDX(p));
.Lxm_done_g4:
	s_ashr_i32 s11, s10, 31
	s_lshl_b64 s[14:15], s[10:11], 11
	v_lshl_add_u64 v[138:139], v[134:135], 0, s[14:15]
	v_add_co_u32_e32 v0, vcc, s94, v138
	s_ashr_i32 s13, s12, 31
	s_nop 0
	v_addc_co_u32_e32 v1, vcc, 0, v139, vcc
	v_add_co_u32_e32 v2, vcc, s72, v138
	s_lshl_b64 s[16:17], s[12:13], 18
	s_nop 0
	v_addc_co_u32_e32 v3, vcc, 0, v139, vcc
	v_add_co_u32_e32 v4, vcc, s73, v138
	v_lshl_add_u64 v[140:141], v[136:137], 0, s[16:17]
	s_nop 0
	v_addc_co_u32_e32 v5, vcc, 0, v139, vcc
	v_add_co_u32_e32 v6, vcc, s94, v140
	global_load_dwordx4 v[14:17], v[138:139], off
	s_nop 0
	v_addc_co_u32_e32 v7, vcc, 0, v141, vcc
	v_add_co_u32_e32 v8, vcc, s72, v140
	global_load_dwordx4 v[18:21], v[0:1], off
	s_nop 0
	v_addc_co_u32_e32 v9, vcc, 0, v141, vcc
	v_add_co_u32_e32 v10, vcc, s73, v140
	global_load_dwordx4 v[22:25], v[2:3], off
	s_nop 0
	v_addc_co_u32_e32 v11, vcc, 0, v141, vcc
	global_load_dwordx4 v[26:29], v[4:5], off
	global_load_dwordx4 v[30:33], v[140:141], off
	global_load_dwordx4 v[34:37], v[6:7], off
	global_load_dwordx4 v[104:107], v[8:9], off
	global_load_dwordx4 v[108:111], v[10:11], off
	global_load_dwordx4 v[40:43], v[138:139], off offset:128
	global_load_dwordx4 v[44:47], v[140:141], off offset:128
	global_load_dwordx4 v[48:51], v[0:1], off offset:128
	global_load_dwordx4 v[52:55], v[2:3], off offset:128
	global_load_dwordx4 v[56:59], v[4:5], off offset:128
	global_load_dwordx4 v[60:63], v[6:7], off offset:128
	global_load_dwordx4 v[68:71], v[8:9], off offset:128
	global_load_dwordx4 v[72:75], v[10:11], off offset:128
	s_barrier
	global_load_dwordx4 v[80:83], v[0:1], off offset:256
	global_load_dwordx4 v[84:87], v[2:3], off offset:256
	global_load_dwordx4 v[64:67], v[138:139], off offset:256
	global_load_dwordx4 v[76:79], v[140:141], off offset:256
	global_load_dwordx4 v[88:91], v[4:5], off offset:256
	global_load_dwordx4 v[92:95], v[6:7], off offset:256
	global_load_dwordx4 v[96:99], v[8:9], off offset:256
	global_load_dwordx4 v[100:103], v[10:11], off offset:256
	v_mov_b32_e32 v0, 0
	s_mov_b32 s11, 0
	v_mov_b32_e32 v1, v0
	v_mov_b32_e32 v2, v0
	v_mov_b32_e32 v3, v0
	v_mov_b32_e32 v8, v0
	v_mov_b32_e32 v9, v0
	v_mov_b32_e32 v10, v0
	v_mov_b32_e32 v11, v0
	v_mov_b32_e32 v4, v0
	v_mov_b32_e32 v5, v0
	v_mov_b32_e32 v6, v0
	v_mov_b32_e32 v7, v0
	v_mov_b32_e32 v12, v0
	v_mov_b32_e32 v13, v0
	v_mov_b32_e32 v38, v0
	v_mov_b32_e32 v39, v0
	v_mov_b32_e32 v112, v0
	v_mov_b32_e32 v113, v0
	v_mov_b32_e32 v114, v0
	v_mov_b32_e32 v115, v0
	v_mov_b32_e32 v120, v0
	v_mov_b32_e32 v121, v0
	v_mov_b32_e32 v122, v0
	v_mov_b32_e32 v123, v0
	v_mov_b32_e32 v116, v0
	v_mov_b32_e32 v117, v0
	v_mov_b32_e32 v118, v0
	v_mov_b32_e32 v119, v0
	v_mov_b32_e32 v124, v0
	v_mov_b32_e32 v125, v0
	v_mov_b32_e32 v126, v0
	v_mov_b32_e32 v127, v0
	s_waitcnt vmcnt(23)
	ds_write_b128 v147, v[14:17]
	s_waitcnt vmcnt(19)
	ds_write_b128 v147, v[30:33] offset:16384
	ds_write_b128 v147, v[18:21] offset:4096
	ds_write_b128 v147, v[22:25] offset:8192
	ds_write_b128 v147, v[26:29] offset:12288
	s_waitcnt vmcnt(18)
	ds_write_b128 v147, v[34:37] offset:20480
	s_waitcnt vmcnt(17)
	ds_write_b128 v147, v[104:107] offset:24576
	s_waitcnt vmcnt(16)
	ds_write_b128 v147, v[108:111] offset:28672
	v_mov_b32_e32 v14, v0
	v_mov_b32_e32 v15, v0
	v_mov_b32_e32 v16, v0
	v_mov_b32_e32 v17, v0
	v_mov_b32_e32 v18, v0
	v_mov_b32_e32 v19, v0
	v_mov_b32_e32 v24, v0
	v_mov_b32_e32 v25, v0
	v_mov_b32_e32 v26, v0
	v_mov_b32_e32 v27, v0
	v_mov_b32_e32 v20, v0
	v_mov_b32_e32 v21, v0
	v_mov_b32_e32 v22, v0
	v_mov_b32_e32 v23, v0
	v_mov_b32_e32 v28, v0
	v_mov_b32_e32 v29, v0
	v_mov_b32_e32 v30, v0
	v_mov_b32_e32 v31, v0
	v_mov_b32_e32 v32, v0
	v_mov_b32_e32 v33, v0
	v_mov_b32_e32 v34, v0
	v_mov_b32_e32 v35, v0
	v_mov_b32_e32 v104, v0
	v_mov_b32_e32 v105, v0
	v_mov_b32_e32 v106, v0
	v_mov_b32_e32 v107, v0
	v_mov_b32_e32 v36, v0
	v_mov_b32_e32 v37, v0
	v_mov_b32_e32 v108, v0
	v_mov_b32_e32 v109, v0
	v_mov_b32_e32 v110, v0
	v_mov_b32_e32 v111, v0
	s_waitcnt lgkmcnt(0)
	s_barrier
	s_bitcmp1_b32 s95, 8
	s_cbranch_scc1 .Lprio_1398
	s_setprio 1

; template <int NJ>
; __device__ __forceinline__ void gemm_tile(const f16* __restrict__ A, int lda, const f16* __restrict__ Bt, int ldb,
;                                           int K, f32x4 (&acc)[4][NJ], f16* sA, f16* sB, const int tid) {
;     ...
;   G_LOAD(ra0, rb0, 0)
;   if (K > 64) G_LOAD(ra1, rb1, 64)
;   __syncthreads();
;   G_STORE(ra0, rb0, 0)
;   if (K > 128) G_LOAD(ra0, rb0, 128)
;   __syncthreads();
; template <int NJ>
; __device__ __forceinline__ void gres_tile(const Params& p, const f16* A, int lda, const f16* W, int K, const float* mod,
;                                           bool first_in, f16* sA, f16* sB, int m0, int n0) {
;   const int lane = TIDX(p) & 63, wave = TIDX(p) >> 6, wm = wave >> 1, wn = wave & 1;
;   f32x4 acc[4][NJ];
;   zero_acc<NJ>(acc);
;   gemm_tile<NJ>(A + (size_t)m0 * lda, lda, W + (size_t)n0 * K, K, K, acc, sA, sB, TIDX(p));
.Lxm_g5:
	s_ashr_i32 s6, s10, 31
	s_lshr_b32 s6, s6, 29
	s_add_i32 s7, s10, s6
	s_lshl_b32 s6, s7, 4
	s_and_b32 s6, s6, 0xffffff80
	v_mad_i64_i32 v[146:147], s[12:13], s6, v191, v[142:143]
	v_add_co_u32_e32 v2, vcc, 0x2c000, v146
	s_and_b32 s7, s7, -8
	s_nop 0
	v_addc_co_u32_e32 v3, vcc, 0, v147, vcc
	s_sub_i32 s7, s10, s7
	v_add_co_u32_e32 v4, vcc, s97, v146
	s_mul_i32 s10, s7, 0x58000
	s_nop 0
	v_addc_co_u32_e32 v5, vcc, 0, v147, vcc
	s_ashr_i32 s11, s10, 31
	v_add_co_u32_e32 v6, vcc, 0x84000, v146
	v_lshl_add_u64 v[148:149], s[10:11], 1, v[144:145]
	s_nop 0
	v_addc_co_u32_e32 v7, vcc, 0, v147, vcc
	v_add_co_u32_e32 v8, vcc, s81, v148
	global_load_dwordx4 v[82:85], v[146:147], off
	s_nop 0
	v_addc_co_u32_e32 v9, vcc, 0, v149, vcc
	v_add_co_u32_e32 v10, vcc, s97, v148
	global_load_dwordx4 v[86:89], v[2:3], off
	s_nop 0
	v_addc_co_u32_e32 v11, vcc, 0, v149, vcc
	v_add_co_u32_e32 v12, vcc, s27, v148
	global_load_dwordx4 v[90:93], v[4:5], off
	s_nop 0
	v_addc_co_u32_e32 v13, vcc, 0, v149, vcc
	global_load_dwordx4 v[94:97], v[6:7], off
	global_load_dwordx4 v[98:101], v[148:149], off
	global_load_dwordx4 v[102:105], v[8:9], off
	global_load_dwordx4 v[106:109], v[10:11], off
	global_load_dwordx4 v[110:113], v[12:13], off
	global_load_dwordx4 v[18:21], v[146:147], off offset:128
	global_load_dwordx4 v[26:29], v[2:3], off offset:128
	global_load_dwordx4 v[22:25], v[148:149], off offset:128
	global_load_dwordx4 v[30:33], v[4:5], off offset:128
	global_load_dwordx4 v[34:37], v[6:7], off offset:128
	global_load_dwordx4 v[38:41], v[8:9], off offset:128
	global_load_dwordx4 v[46:49], v[10:11], off offset:128
	global_load_dwordx4 v[50:53], v[12:13], off offset:128
	s_barrier
	global_load_dwordx4 v[58:61], v[2:3], off offset:256
	global_load_dwordx4 v[62:65], v[4:5], off offset:256
	global_load_dwordx4 v[42:45], v[146:147], off offset:256
	global_load_dwordx4 v[54:57], v[148:149], off offset:256
	global_load_dwordx4 v[66:69], v[6:7], off offset:256
	global_load_dwordx4 v[70:73], v[8:9], off offset:256
	global_load_dwordx4 v[74:77], v[10:11], off offset:256
	global_load_dwordx4 v[78:81], v[12:13], off offset:256
	v_mov_b32_e32 v2, 0
	s_mov_b32 s10, 0
	v_mov_b32_e32 v3, v2
	v_mov_b32_e32 v4, v2
	v_mov_b32_e32 v5, v2
	v_mov_b32_e32 v6, v2
	v_mov_b32_e32 v7, v2
	v_mov_b32_e32 v8, v2
	v_mov_b32_e32 v9, v2
	v_mov_b32_e32 v10, v2
	v_mov_b32_e32 v11, v2
	v_mov_b32_e32 v12, v2
	v_mov_b32_e32 v13, v2
	v_mov_b32_e32 v14, v2
	v_mov_b32_e32 v15, v2
	v_mov_b32_e32 v16, v2
	v_mov_b32_e32 v17, v2
	v_mov_b32_e32 v114, v2
	v_mov_b32_e32 v115, v2
	v_mov_b32_e32 v116, v2
	v_mov_b32_e32 v117, v2
	v_mov_b32_e32 v118, v2
	v_mov_b32_e32 v119, v2
	v_mov_b32_e32 v120, v2
	v_mov_b32_e32 v121, v2
	v_mov_b32_e32 v122, v2
	v_mov_b32_e32 v123, v2
	v_mov_b32_e32 v124, v2
	v_mov_b32_e32 v125, v2
	v_mov_b32_e32 v126, v2
	v_mov_b32_e32 v127, v2
	v_mov_b32_e32 v128, v2
	v_mov_b32_e32 v129, v2
	s_waitcnt vmcnt(23)
	ds_write_b128 v161, v[82:85]
	s_waitcnt vmcnt(22)
	ds_write_b128 v161, v[86:89] offset:4096
	s_waitcnt vmcnt(19)
	ds_write_b128 v161, v[98:101] offset:16384
	ds_write_b128 v161, v[90:93] offset:8192
	ds_write_b128 v161, v[94:97] offset:12288
	s_waitcnt vmcnt(18)
	ds_write_b128 v161, v[102:105] offset:20480
	s_waitcnt vmcnt(17)
	ds_write_b128 v161, v[106:109] offset:24576
	s_waitcnt vmcnt(16)
	ds_write_b128 v161, v[110:113] offset:28672
	s_waitcnt lgkmcnt(0)
	s_barrier
	v_mov_b32_e32 v82, v2
	v_mov_b32_e32 v83, v2
	v_mov_b32_e32 v84, v2
	v_mov_b32_e32 v85, v2
	v_mov_b32_e32 v86, v2
	v_mov_b32_e32 v87, v2
	v_mov_b32_e32 v88, v2
	v_mov_b32_e32 v89, v2
	v_mov_b32_e32 v90, v2
	v_mov_b32_e32 v91, v2
	v_mov_b32_e32 v92, v2
	v_mov_b32_e32 v93, v2
	v_mov_b32_e32 v94, v2
	v_mov_b32_e32 v95, v2
	v_mov_b32_e32 v96, v2
	v_mov_b32_e32 v97, v2
	v_mov_b32_e32 v98, v2
	v_mov_b32_e32 v99, v2
	v_mov_b32_e32 v100, v2
	v_mov_b32_e32 v101, v2
	v_mov_b32_e32 v102, v2
	v_mov_b32_e32 v103, v2
	v_mov_b32_e32 v104, v2
	v_mov_b32_e32 v105, v2
	v_mov_b32_e32 v106, v2
	v_mov_b32_e32 v107, v2
	v_mov_b32_e32 v108, v2
	v_mov_b32_e32 v109, v2
	v_mov_b32_e32 v110, v2
	v_mov_b32_e32 v111, v2
	v_mov_b32_e32 v112, v2
	v_mov_b32_e32 v113, v2
	s_bitcmp1_b32 s95, 8
	s_cbranch_scc1 .Lprio_1457
	s_setprio 1
